# P6: workgroups staggered in 4 groups (0/7.7/15.5/23 us) at phase start to spread epilogue store bursts
# baseline (speedup 1.0000x reference)
; template <class Epi>
; __device__ __forceinline__ void gemm_phase(const u16* A, const u16* Bt, int K, int nN, Epi epi) {
;   {
;     int x = epi.p.vx, j = epi.p.vj;
;     int li = j;
;     int mg = li / (nN * 8), rem = li % (nN * 8);
;     int brow = (x * 32 + mg * 8 + (rem & 7)) * 256, bcol = (rem >> 3) * 256;
;     for (int rd = 0; rd < nN; ++rd) {
;       int nbrow = 0, nbcol = 0;
;       bool has_next = rd + 1 < nN;
;       if (has_next) {
;         int l2 = (rd + 1) * 32 + j;
;         int mg2 = l2 / (nN * 8), rem2 = l2 % (nN * 8);
;         nbrow = (x * 32 + mg2 * 8 + (rem2 & 7)) * 256; nbcol = (rem2 >> 3) * 256;
;       }
;       gemm_tile(A, Bt, K, brow, bcol, rd == 0, has_next, nbrow, nbcol, epi);
.LBB0_578:
	s_or_b64 exec, exec, s[0:1]
	s_add_u32 s25, s34, 0x1e200000
	s_mul_hi_i32 s0, s80, 0x2e8ba2e9
	s_addc_u32 s27, s35, 0
	s_lshr_b32 s1, s0, 31
	s_ashr_i32 s0, s0, 5
	s_add_i32 s0, s0, s1
	s_mul_i32 s1, s0, 0xb0
	s_sub_i32 s1, s80, s1
	s_lshl_b32 s0, s0, 3
	s_add_i32 s0, s0, s81
	s_and_b32 s2, s1, 7
	s_or_b32 s0, s0, s2
	s_lshl_b32 s2, s0, 8
	s_lshl_b32 s0, s1, 5
	s_and_b32 s0, s0, 0xffffff00
	s_mov_b32 s1, 0
	v_mov_b32_e32 v129, 0
	s_mov_b64 s[10:11], 0x80
	s_movk_i32 s60, 0x3c0
	s_mov_b64 s[12:13], 0x16000080
	s_mov_b64 s[14:15], 0x1e200100
	s_mov_b64 s[16:17], 0x16000100
	s_mov_b64 s[18:19], 0x1e200180
	s_mov_b64 s[20:21], 0x16000180
	s_mov_b64 s[22:23], 0x780
	s_movk_i32 s61, 0x100
	s_mov_b32 s24, 0x3a800000
	s_mov_b32 s26, 0x358637bd
	s_mov_b32 s62, 0x800000
	s_movk_i32 s63, 0x1600
	v_mov_b32_e32 v162, 1
	s_mov_b32 s101, -1
	s_waitcnt lgkmcnt(0)
	s_barrier
	s_and_b32 s98, s80, 3
	s_cmp_eq_u32 s98, 0
	s_cbranch_scc1 .Lmy_stg_done_P6
.Lmy_stg_loop_P6:
	s_sleep 127
	s_sleep 127
	s_sub_u32 s98, s98, 1
	s_cmp_lg_u32 s98, 0
	s_cbranch_scc1 .Lmy_stg_loop_P6
